# MLA softmax fast path without the per-tile row max (row-sum range check after exp, recentre/redo path kept), leading-half barrier moved ahead of the last three P.V MFMAs
# speedup vs baseline: 1.0312x; 1.0096x over previous
; #define SBAR() __builtin_amdgcn_sched_barrier(0)
; template <int OFF> DEV s16x4 tr_read(int vb) { s16x4 r; asm volatile("ds_read_b64_tr_b16 %0, %1 offset:%2" : "=&v"(r) : "v"(vb), "i"(OFF) : "memory"); return r; }
; template <int D0, bool SPLIT = true> DEV void pv_one(f32x16& od, int vb, bf16x8 pa0, bf16x8 pa1, bf16x8 pa2, bf16x8 pa3) {
;     ...
;   } else {
;     const s16x4 l0 = tr_read<v_rd_off(D0, 0, 0)>(vb), h0 = tr_read<v_rd_off(D0, 0, 1)>(vb), l1 = tr_read<v_rd_off(D0, 1, 0)>(vb), h1 = tr_read<v_rd_off(D0, 1, 1)>(vb);
;     const s16x4 l2 = tr_read<v_rd_off(D0, 2, 0)>(vb), h2 = tr_read<v_rd_off(D0, 2, 1)>(vb), l3 = tr_read<v_rd_off(D0, 3, 0)>(vb), h3 = tr_read<v_rd_off(D0, 3, 1)>(vb);
;     asm volatile("s_waitcnt lgkmcnt(0)" ::: "memory"); SBAR();
;     od = __builtin_amdgcn_mfma_f32_32x32x16_bf16(pa0, PK(l0, h0), od, 0, 0, 0);
;     od = __builtin_amdgcn_mfma_f32_32x32x16_bf16(pa1, PK(l1, h1), od, 0, 0, 0);
;     od = __builtin_amdgcn_mfma_f32_32x32x16_bf16(pa2, PK(l2, h2), od, 0, 0, 0);
;     od = __builtin_amdgcn_mfma_f32_32x32x16_bf16(pa3, PK(l3, h3), od, 0, 0, 0);
;   }
; template <bool WIN>
; DEV void partialSM(f32x16& p0, f32x16& p1, float& m_reg, float& mn, float& alpha, const float C, const float thr_raw, int kdiff) {
;     ...
;   const float mnC = -mn * C;
; #pragma unroll
;   for (int r = 0; r < 16; ++r) p0[r] = fmaf(p0[r], C, mnC);
; #pragma unroll
;   for (int r = 0; r < 16; ++r) p1[r] = fmaf(p1[r], C, mnC);
; #pragma unroll
;   for (int r = 0; r < 16; ++r) p0[r] = __builtin_amdgcn_exp2f(p0[r]);
; }
; DEV void finishSM(f32x16& p0, f32x16& p1, float alpha, float& l_reg, bf16x8& pa0, bf16x8& pa1, bf16x8& pa2, bf16x8& pa3) {
; #pragma unroll
;   for (int r = 0; r < 16; ++r) p1[r] = __builtin_amdgcn_exp2f(p1[r]);
;   float ps = 0;
; #pragma unroll
;   for (int r = 0; r < 16; ++r) ps += p0[r];
; #pragma unroll
;   for (int r = 0; r < 16; ++r) ps += p1[r];
;   { auto rr = __builtin_amdgcn_permlane32_swap(__float_as_uint(ps), __float_as_uint(ps), false, false);
;     ps = __uint_as_float(rr[0]) + __uint_as_float(rr[1]); }
;   l_reg = l_reg * alpha + ps;
;     ...
;   PK4(p0, 0, pa0); PK4(p0, 8, pa1); PK4(p1, 0, pa2); PK4(p1, 8, pa3);
;     ...
; }
.Lmla_lead_mid:
	s_cmp_eq_u32 s24, 0
	s_cbranch_scc1 .Lmla_first
	v_mov_b32_e32 v188, 1.0
.Lmla_exp:
	v_mov_b32_e32 v189, v79
	v_exp_f32_e32 v79, v80
	v_exp_f32_e32 v190, v81
	v_exp_f32_e32 v82, v82
	v_exp_f32_e32 v83, v83
	v_exp_f32_e32 v84, v84
	v_exp_f32_e32 v191, v68
	v_add_f32_e32 v68, 0, v79
	v_exp_f32_e32 v85, v85
	v_add_f32_e32 v68, v190, v68
	v_exp_f32_e32 v86, v86
	v_add_f32_e32 v68, v82, v68
	v_exp_f32_e32 v87, v87
	v_add_f32_e32 v68, v83, v68
	v_exp_f32_e32 v88, v88
	v_add_f32_e32 v68, v84, v68
	v_exp_f32_e32 v89, v89
	v_add_f32_e32 v68, v85, v68
	v_exp_f32_e32 v90, v90
	v_add_f32_e32 v68, v86, v68
	v_exp_f32_e32 v91, v91
	v_add_f32_e32 v68, v87, v68
	v_exp_f32_e32 v92, v92
	v_add_f32_e32 v68, v88, v68
	v_exp_f32_e32 v93, v93
	v_add_f32_e32 v68, v89, v68
	v_exp_f32_e32 v94, v94
	v_add_f32_e32 v68, v90, v68
	v_exp_f32_e32 v95, v95
	v_add_f32_e32 v68, v91, v68
	v_exp_f32_e32 v64, v64
	v_add_f32_e32 v68, v92, v68
	v_exp_f32_e32 v65, v65
	v_add_f32_e32 v68, v93, v68
	v_exp_f32_e32 v66, v66
	v_add_f32_e32 v68, v94, v68
	v_exp_f32_e32 v67, v67
	v_add_f32_e32 v68, v95, v68
	v_add_f32_e32 v68, v64, v68
	v_exp_f32_e32 v198, v69
	v_add_f32_e32 v68, v65, v68
	v_exp_f32_e32 v199, v70
	v_add_f32_e32 v68, v66, v68
	v_exp_f32_e32 v200, v71
	v_add_f32_e32 v68, v67, v68
	v_exp_f32_e32 v201, v72
	v_add_f32_e32 v68, v191, v68
	v_exp_f32_e32 v202, v73
	v_add_f32_e32 v68, v198, v68
	v_exp_f32_e32 v203, v74
	v_add_f32_e32 v68, v199, v68
	v_exp_f32_e32 v213, v75
	v_add_f32_e32 v68, v200, v68
	v_exp_f32_e32 v214, v76
	v_add_f32_e32 v68, v201, v68
	v_exp_f32_e32 v215, v77
	v_add_f32_e32 v68, v202, v68
	v_exp_f32_e32 v216, v78
	v_add_f32_e32 v68, v203, v68
	v_exp_f32_e32 v189, v189
	v_add_f32_e32 v68, v213, v68
	v_add_f32_e32 v68, v214, v68
	v_add_f32_e32 v68, v215, v68
	v_add_f32_e32 v68, v216, v68
	v_add_f32_e32 v80, v189, v68
	v_mov_b32_e32 v81, v80
	v_cvt_pk_bf16_f32 v68, v79, v190
	v_cvt_pk_bf16_f32 v69, v82, v83
	v_cvt_pk_bf16_f32 v70, v84, v85
	v_cvt_pk_bf16_f32 v71, v86, v87
	v_cvt_pk_bf16_f32 v72, v88, v89
	v_cvt_pk_bf16_f32 v73, v90, v91
	v_cvt_pk_bf16_f32 v74, v92, v93
	v_cvt_pk_bf16_f32 v75, v94, v95
	v_cvt_pk_bf16_f32 v76, v64, v65
	v_cvt_pk_bf16_f32 v77, v66, v67
	v_cvt_pk_bf16_f32 v78, v191, v198
	v_cvt_pk_bf16_f32 v79, v199, v200
	v_cvt_pk_bf16_f32 v64, v201, v202
	v_cvt_pk_bf16_f32 v65, v203, v213
	v_cvt_pk_bf16_f32 v66, v214, v215
	v_cvt_pk_bf16_f32 v67, v216, v189
	v_permlane32_swap_b32_e32 v80, v81
	v_permlane32_swap_b32_e32 v68, v70
	v_permlane32_swap_b32_e32 v69, v71
	v_permlane32_swap_b32_e32 v72, v74
	v_permlane32_swap_b32_e32 v73, v75
	v_permlane32_swap_b32_e32 v76, v78
	v_permlane32_swap_b32_e32 v77, v79
	v_permlane32_swap_b32_e32 v64, v66
	v_permlane32_swap_b32_e32 v65, v67
	v_add_f32_e32 v144, v80, v81
	v_cmp_ge_f32_e32 vcc, 0x47800000, v144
	s_cmp_eq_u64 vcc, exec
	s_cbranch_scc1 .Lmla_ok
	s_bitcmp1_b32 s100, 2
	s_cbranch_scc0 .Lmla_redo
.Lmla_ok:
	s_bitset0_b32 s100, 2
	v_fmac_f32_e32 v144, v187, v188
	s_add_i32 s24, s24, 1
	s_lshl_b32 s2, s101, 14
	s_cmp_eq_u32 s101, 2
	s_cselect_b32 s2, 0x15000, s2
	v_add_u32_e32 v145, s2, v177
	ds_read_b64_tr_b16 v[80:81], v145 offset:0
	ds_read_b64_tr_b16 v[82:83], v145 offset:0x800
	ds_read_b64_tr_b16 v[84:85], v145 offset:0x1000
	ds_read_b64_tr_b16 v[86:87], v145 offset:0x1800
	ds_read_b64_tr_b16 v[88:89], v145 offset:0x2000
	ds_read_b64_tr_b16 v[90:91], v145 offset:0x2800
	ds_read_b64_tr_b16 v[92:93], v145 offset:0x3000
	ds_read_b64_tr_b16 v[94:95], v145 offset:0x3800
	s_waitcnt lgkmcnt(0)
	s_nop 0
	v_mfma_f32_32x32x16_bf16 v[0:15], v[68:71], v[80:83], v[0:15]
	ds_read_b64_tr_b16 v[80:81], v145 offset:0x200
	ds_read_b64_tr_b16 v[82:83], v145 offset:0xa00
	v_mfma_f32_32x32x16_bf16 v[0:15], v[72:75], v[84:87], v[0:15]
	ds_read_b64_tr_b16 v[84:85], v145 offset:0x1200
	ds_read_b64_tr_b16 v[86:87], v145 offset:0x1a00
	v_mfma_f32_32x32x16_bf16 v[0:15], v[76:79], v[88:91], v[0:15]
	ds_read_b64_tr_b16 v[88:89], v145 offset:0x2200
	ds_read_b64_tr_b16 v[90:91], v145 offset:0x2a00
	v_mfma_f32_32x32x16_bf16 v[0:15], v[64:67], v[92:95], v[0:15]
	ds_read_b64_tr_b16 v[92:93], v145 offset:0x3200
	ds_read_b64_tr_b16 v[94:95], v145 offset:0x3a00
	s_waitcnt lgkmcnt(0)
	v_mfma_f32_32x32x16_bf16 v[48:63], v[68:71], v[80:83], v[48:63]
	ds_read_b64_tr_b16 v[80:81], v145 offset:0x400
	ds_read_b64_tr_b16 v[82:83], v145 offset:0xc00
	v_mfma_f32_32x32x16_bf16 v[48:63], v[72:75], v[84:87], v[48:63]
	ds_read_b64_tr_b16 v[84:85], v145 offset:0x1400
	ds_read_b64_tr_b16 v[86:87], v145 offset:0x1c00
	v_mfma_f32_32x32x16_bf16 v[48:63], v[76:79], v[88:91], v[48:63]
	ds_read_b64_tr_b16 v[88:89], v145 offset:0x2400
	ds_read_b64_tr_b16 v[90:91], v145 offset:0x2c00
	v_mfma_f32_32x32x16_bf16 v[48:63], v[64:67], v[92:95], v[48:63]
	ds_read_b64_tr_b16 v[92:93], v145 offset:0x3400
	ds_read_b64_tr_b16 v[94:95], v145 offset:0x3c00
	s_waitcnt lgkmcnt(0)
	v_mfma_f32_32x32x16_bf16 v[32:47], v[68:71], v[80:83], v[32:47]
	ds_read_b64_tr_b16 v[80:81], v145 offset:0x600
	ds_read_b64_tr_b16 v[82:83], v145 offset:0xe00
	v_mfma_f32_32x32x16_bf16 v[32:47], v[72:75], v[84:87], v[32:47]
	ds_read_b64_tr_b16 v[84:85], v145 offset:0x1600
	ds_read_b64_tr_b16 v[86:87], v145 offset:0x1e00
	v_mfma_f32_32x32x16_bf16 v[32:47], v[76:79], v[88:91], v[32:47]
	ds_read_b64_tr_b16 v[88:89], v145 offset:0x2600
	ds_read_b64_tr_b16 v[90:91], v145 offset:0x2e00
	v_mfma_f32_32x32x16_bf16 v[32:47], v[64:67], v[92:95], v[32:47]
	ds_read_b64_tr_b16 v[92:93], v145 offset:0x3600
	ds_read_b64_tr_b16 v[94:95], v145 offset:0x3e00
	s_waitcnt lgkmcnt(0)
	v_mfma_f32_32x32x16_bf16 v[16:31], v[68:71], v[80:83], v[16:31]
	s_mov_b64 s[2:3], 0x20000
	v_lshl_add_u64 v[164:165], v[164:165], 0, s[62:63]
	v_lshl_add_u64 v[166:167], v[166:167], 0, s[62:63]
	v_lshl_add_u64 v[168:169], v[168:169], 0, s[62:63]
	v_lshl_add_u64 v[170:171], v[170:171], 0, s[2:3]
	s_add_i32 s101, s101, 1
	s_cmp_eq_u32 s101, 3
	s_cselect_b32 s101, 0, s101
	s_waitcnt lgkmcnt(0)
	s_bitcmp1_b32 s100, 0
	s_cbranch_scc1 .Lmla_trail_end
	s_barrier
; #define SBAR() __builtin_amdgcn_sched_barrier(0)
; template <bool WIN>
; DEV void partialSM(f32x16& p0, f32x16& p1, float& m_reg, float& mn, float& alpha, const float C, const float thr_raw, int kdiff) {
;     ...
;   float pmax = p0[0];
; #pragma unroll
;   for (int r = 1; r < 16; ++r) pmax = fmaxf(pmax, p0[r]);
; #pragma unroll
;   for (int r = 0; r < 16; ++r) pmax = fmaxf(pmax, p1[r]);
;   { auto rr = __builtin_amdgcn_permlane32_swap(__float_as_uint(pmax), __float_as_uint(pmax), false, false);
;     pmax = fmaxf(__uint_as_float(rr[0]), __uint_as_float(rr[1])); }
;   if (__builtin_expect(__all(pmax - m_reg <= thr_raw), 1)) { mn = m_reg; alpha = 1.f; }
;   else { mn = fmaxf(m_reg, pmax); alpha = __builtin_amdgcn_exp2f((m_reg - mn) * C); m_reg = mn; }
; template <int DQK, int NQR>
; DEV void qkt(f32x16& p0, f32x16& p1, const char* Ks, const bf16x8* qr, const char* qlds_, int r32, int hi) {
;   constexpr int KROW = ACfg<DQK>::KROW;
;   unsigned qa = (unsigned)(uintptr_t)qlds_; asm volatile("" : "+v"(qa));
;   const __attribute__((address_space(3))) char* qlds = (const __attribute__((address_space(3))) char*)qa;
; #pragma unroll
;   for (int r = 0; r < 16; ++r) { p0[r] = 0.f; p1[r] = 0.f; }
; #pragma unroll
;   for (int d0 = 0; d0 < DQK / 16; ++d0) {
;     const int cb = (d0 * 16 + hi * 8) * 2;
;     bf16x8 b0 = *reinterpret_cast<const bf16x8*>(Ks + r32 * KROW + cb);
;     bf16x8 b1 = *reinterpret_cast<const bf16x8*>(Ks + (32 + r32) * KROW + cb);
;     bf16x8 q;
;     if (d0 < NQR) q = qr[d0 < NQR ? d0 : 0]; else q = *reinterpret_cast<const __attribute__((address_space(3))) bf16x8*>(qlds + (d0 - NQR) * 1024);
;     p0 = __builtin_amdgcn_mfma_f32_32x32x16_bf16(b0, q, p0, 0, 0, 0);
;     p1 = __builtin_amdgcn_mfma_f32_32x32x16_bf16(b1, q, p1, 0, 0, 0);
;     if (NQR < DQK / 16 && (d0 & 3) == 3) SBAR();
;   }
; }
.Lmla_trail_end:
	v_mfma_f32_32x32x16_bf16 v[16:31], v[72:75], v[84:87], v[16:31]
	v_mfma_f32_32x32x16_bf16 v[16:31], v[76:79], v[88:91], v[16:31]
	v_mfma_f32_32x32x16_bf16 v[16:31], v[64:67], v[92:95], v[16:31]
	s_cmp_eq_u32 s20, s24
	s_cbranch_scc1 .LBB0_471
	v_mov_b32_e32 v187, v144
	s_branch .LBB0_461
.Lmla_first:
	v_max_f32_e32 v188, v81, v81
	v_max_f32_e32 v189, v80, v80
	v_max_f32_e32 v188, v189, v188
	v_max3_f32 v188, v188, v82, v83
	v_max3_f32 v188, v188, v84, v85
	v_max3_f32 v188, v188, v86, v87
	v_max3_f32 v188, v188, v88, v89
	v_max3_f32 v188, v188, v90, v91
	v_max3_f32 v188, v188, v92, v93
	v_max3_f32 v188, v188, v94, v95
	v_max3_f32 v188, v188, v64, v65
	v_max3_f32 v188, v188, v66, v67
	v_max3_f32 v188, v188, v68, v69
	v_max3_f32 v188, v188, v70, v71
	v_max3_f32 v188, v188, v72, v73
	v_max3_f32 v188, v188, v74, v75
	v_max3_f32 v188, v188, v76, v77
	v_max3_f32 v188, v188, v78, v79
	v_mov_b32_e32 v189, v188
	s_nop 1
	v_permlane32_swap_b32_e32 v188, v189
	v_max_f32_e32 v189, v189, v189
	v_max_f32_e32 v188, v188, v188
	v_max_f32_e32 v188, v188, v189
	v_mov_b32_e32 v189, v188
	v_mov_b32_e32 v188, 1.0
	v_add_f32_e32 v178, v178, v189
	v_sub_f32_e32 v80, v80, v189
	v_sub_f32_e32 v81, v81, v189
	v_sub_f32_e32 v82, v82, v189
	v_sub_f32_e32 v83, v83, v189
	v_sub_f32_e32 v84, v84, v189
	v_sub_f32_e32 v85, v85, v189
	v_sub_f32_e32 v86, v86, v189
	v_sub_f32_e32 v87, v87, v189
	v_sub_f32_e32 v88, v88, v189
	v_sub_f32_e32 v89, v89, v189
	v_sub_f32_e32 v90, v90, v189
	v_sub_f32_e32 v91, v91, v189
	v_sub_f32_e32 v92, v92, v189
	v_sub_f32_e32 v93, v93, v189
	v_sub_f32_e32 v94, v94, v189
	v_sub_f32_e32 v95, v95, v189
	v_sub_f32_e32 v64, v64, v189
	v_sub_f32_e32 v65, v65, v189
	v_sub_f32_e32 v66, v66, v189
	v_sub_f32_e32 v67, v67, v189
	v_sub_f32_e32 v68, v68, v189
	v_sub_f32_e32 v69, v69, v189
	v_sub_f32_e32 v70, v70, v189
	v_sub_f32_e32 v71, v71, v189
	v_sub_f32_e32 v72, v72, v189
	v_sub_f32_e32 v73, v73, v189
	v_sub_f32_e32 v74, v74, v189
	v_sub_f32_e32 v75, v75, v189
	v_sub_f32_e32 v76, v76, v189
	v_sub_f32_e32 v77, v77, v189
	v_sub_f32_e32 v78, v78, v189
	v_sub_f32_e32 v79, v79, v189
	v_sub_f32_e32 v226, v226, v189
	v_sub_f32_e32 v227, v227, v189
	v_sub_f32_e32 v228, v228, v189
	v_sub_f32_e32 v229, v229, v189
	v_sub_f32_e32 v230, v230, v189
	v_sub_f32_e32 v231, v231, v189
	v_sub_f32_e32 v232, v232, v189
	v_sub_f32_e32 v233, v233, v189
	v_sub_f32_e32 v234, v234, v189
	v_sub_f32_e32 v235, v235, v189
	v_sub_f32_e32 v236, v236, v189
	v_sub_f32_e32 v237, v237, v189
	v_sub_f32_e32 v238, v238, v189
	v_sub_f32_e32 v239, v239, v189
	v_sub_f32_e32 v240, v240, v189
	v_sub_f32_e32 v241, v241, v189
	s_branch .Lmla_exp
.Lmla_redo:
	s_bitset1_b32 s100, 2
	s_mul_i32 s2, s18, 0x6400
	v_add_u32_e32 v202, s2, v186
	ds_read_b128 v[188:191], v202 offset:32768
	ds_read_b128 v[198:201], v202 offset:45568
	s_waitcnt lgkmcnt(0)
	v_mfma_f32_32x32x16_bf16 v[80:95], v[188:191], v[140:143], v[226:241]
	v_mfma_f32_32x32x16_bf16 v[64:79], v[198:201], v[140:143], v[226:241]
	ds_read_b128 v[188:191], v202 offset:32800
	ds_read_b128 v[198:201], v202 offset:45600
	s_waitcnt lgkmcnt(0)
	v_mfma_f32_32x32x16_bf16 v[80:95], v[188:191], v[136:139], v[80:95]
	v_mfma_f32_32x32x16_bf16 v[64:79], v[198:201], v[136:139], v[64:79]
	ds_read_b128 v[188:191], v202 offset:32832
	ds_read_b128 v[198:201], v202 offset:45632
	s_waitcnt lgkmcnt(0)
	v_mfma_f32_32x32x16_bf16 v[80:95], v[188:191], v[132:135], v[80:95]
	v_mfma_f32_32x32x16_bf16 v[64:79], v[198:201], v[132:135], v[64:79]
	ds_read_b128 v[188:191], v202 offset:32864
	ds_read_b128 v[198:201], v202 offset:45664
	s_waitcnt lgkmcnt(0)
	v_mfma_f32_32x32x16_bf16 v[80:95], v[188:191], v[128:131], v[80:95]
	v_mfma_f32_32x32x16_bf16 v[64:79], v[198:201], v[128:131], v[64:79]
	ds_read_b128 v[188:191], v202 offset:32896
	ds_read_b128 v[198:201], v202 offset:45696
	s_waitcnt lgkmcnt(0)
	v_mfma_f32_32x32x16_bf16 v[80:95], v[188:191], v[124:127], v[80:95]
	v_mfma_f32_32x32x16_bf16 v[64:79], v[198:201], v[124:127], v[64:79]
	ds_read_b128 v[188:191], v202 offset:32928
	ds_read_b128 v[198:201], v202 offset:45728
	s_waitcnt lgkmcnt(0)
	v_mfma_f32_32x32x16_bf16 v[80:95], v[188:191], v[120:123], v[80:95]
	v_mfma_f32_32x32x16_bf16 v[64:79], v[198:201], v[120:123], v[64:79]
	ds_read_b128 v[188:191], v202 offset:32960
	ds_read_b128 v[198:201], v202 offset:45760
	s_waitcnt lgkmcnt(0)
	v_mfma_f32_32x32x16_bf16 v[80:95], v[188:191], v[116:119], v[80:95]
	v_mfma_f32_32x32x16_bf16 v[64:79], v[198:201], v[116:119], v[64:79]
	ds_read_b128 v[188:191], v202 offset:32992
	ds_read_b128 v[198:201], v202 offset:45792
	s_waitcnt lgkmcnt(0)
	v_mfma_f32_32x32x16_bf16 v[80:95], v[188:191], v[112:115], v[80:95]
	v_mfma_f32_32x32x16_bf16 v[64:79], v[198:201], v[112:115], v[64:79]
	ds_read_b128 v[188:191], v202 offset:33024
	ds_read_b128 v[198:201], v202 offset:45824
	s_waitcnt lgkmcnt(0)
	v_mfma_f32_32x32x16_bf16 v[80:95], v[188:191], v[108:111], v[80:95]
	v_mfma_f32_32x32x16_bf16 v[64:79], v[198:201], v[108:111], v[64:79]
	ds_read_b128 v[188:191], v202 offset:33056
	ds_read_b128 v[198:201], v202 offset:45856
	s_waitcnt lgkmcnt(0)
; template <bool WIN>
; DEV void partialSM(f32x16& p0, f32x16& p1, float& m_reg, float& mn, float& alpha, const float C, const float thr_raw, int kdiff) {
;     ...
;   float pmax = p0[0];
; #pragma unroll
;   for (int r = 1; r < 16; ++r) pmax = fmaxf(pmax, p0[r]);
; #pragma unroll
;   for (int r = 0; r < 16; ++r) pmax = fmaxf(pmax, p1[r]);
;   { auto rr = __builtin_amdgcn_permlane32_swap(__float_as_uint(pmax), __float_as_uint(pmax), false, false);
;     pmax = fmaxf(__uint_as_float(rr[0]), __uint_as_float(rr[1])); }
;   if (__builtin_expect(__all(pmax - m_reg <= thr_raw), 1)) { mn = m_reg; alpha = 1.f; }
;   else { mn = fmaxf(m_reg, pmax); alpha = __builtin_amdgcn_exp2f((m_reg - mn) * C); m_reg = mn; }
	v_mfma_f32_32x32x16_bf16 v[80:95], v[188:191], v[104:107], v[80:95]
	v_mfma_f32_32x32x16_bf16 v[64:79], v[198:201], v[104:107], v[64:79]
	ds_read_b128 v[188:191], v202 offset:33088
	ds_read_b128 v[198:201], v202 offset:45888
	s_waitcnt lgkmcnt(0)
	v_mfma_f32_32x32x16_bf16 v[80:95], v[188:191], v[100:103], v[80:95]
	v_mfma_f32_32x32x16_bf16 v[64:79], v[198:201], v[100:103], v[64:79]
	ds_read_b128 v[188:191], v202 offset:33120
	ds_read_b128 v[198:201], v202 offset:45920
	s_waitcnt lgkmcnt(0)
	v_mfma_f32_32x32x16_bf16 v[80:95], v[188:191], v[96:99], v[80:95]
	v_mfma_f32_32x32x16_bf16 v[64:79], v[198:201], v[96:99], v[64:79]
	s_nop 7
	s_nop 3
	v_max_f32_e32 v188, v81, v81
	v_max_f32_e32 v189, v80, v80
	v_max_f32_e32 v188, v189, v188
	v_max3_f32 v188, v188, v82, v83
	v_max3_f32 v188, v188, v84, v85
	v_max3_f32 v188, v188, v86, v87
	v_max3_f32 v188, v188, v88, v89
	v_max3_f32 v188, v188, v90, v91
	v_max3_f32 v188, v188, v92, v93
	v_max3_f32 v188, v188, v94, v95
	v_max3_f32 v188, v188, v64, v65
	v_max3_f32 v188, v188, v66, v67
	v_max3_f32 v188, v188, v68, v69
	v_max3_f32 v188, v188, v70, v71
	v_max3_f32 v188, v188, v72, v73
	v_max3_f32 v188, v188, v74, v75
	v_max3_f32 v188, v188, v76, v77
	v_max3_f32 v188, v188, v78, v79
	v_mov_b32_e32 v189, v188
	s_nop 1
	v_permlane32_swap_b32_e32 v188, v189
	v_max_f32_e32 v189, v189, v189
	v_max_f32_e32 v188, v188, v188
	v_max_f32_e32 v188, v188, v189
	v_max_f32_e32 v189, 0, v188
	v_exp_f32_e64 v188, -v189
	v_add_f32_e32 v178, v178, v189
	v_sub_f32_e32 v80, v80, v189
	v_sub_f32_e32 v81, v81, v189
	v_sub_f32_e32 v82, v82, v189
	v_sub_f32_e32 v83, v83, v189
	v_sub_f32_e32 v84, v84, v189
	v_sub_f32_e32 v85, v85, v189
	v_sub_f32_e32 v86, v86, v189
	v_sub_f32_e32 v87, v87, v189
	v_sub_f32_e32 v88, v88, v189
	v_sub_f32_e32 v89, v89, v189
	v_sub_f32_e32 v90, v90, v189
	v_sub_f32_e32 v91, v91, v189
	v_sub_f32_e32 v92, v92, v189
	v_sub_f32_e32 v93, v93, v189
	v_sub_f32_e32 v94, v94, v189
	v_sub_f32_e32 v95, v95, v189
	v_sub_f32_e32 v64, v64, v189
	v_sub_f32_e32 v65, v65, v189
	v_sub_f32_e32 v66, v66, v189
	v_sub_f32_e32 v67, v67, v189
	v_sub_f32_e32 v68, v68, v189
	v_sub_f32_e32 v69, v69, v189
	v_sub_f32_e32 v70, v70, v189
	v_sub_f32_e32 v71, v71, v189
	v_sub_f32_e32 v72, v72, v189
	v_sub_f32_e32 v73, v73, v189
	v_sub_f32_e32 v74, v74, v189
	v_sub_f32_e32 v75, v75, v189
	v_sub_f32_e32 v76, v76, v189
	v_sub_f32_e32 v77, v77, v189
	v_sub_f32_e32 v78, v78, v189
	v_sub_f32_e32 v79, v79, v189
	v_sub_f32_e32 v226, v226, v189
	v_sub_f32_e32 v227, v227, v189
	v_sub_f32_e32 v228, v228, v189
	v_sub_f32_e32 v229, v229, v189
	v_sub_f32_e32 v230, v230, v189
	v_sub_f32_e32 v231, v231, v189
	v_sub_f32_e32 v232, v232, v189
	v_sub_f32_e32 v233, v233, v189
	v_sub_f32_e32 v234, v234, v189
	v_sub_f32_e32 v235, v235, v189
	v_sub_f32_e32 v236, v236, v189
	v_sub_f32_e32 v237, v237, v189
	v_sub_f32_e32 v238, v238, v189
	v_sub_f32_e32 v239, v239, v189
	v_sub_f32_e32 v240, v240, v189
	v_sub_f32_e32 v241, v241, v189
	v_cmp_gt_f32_e32 vcc, 1.0, v188
	s_cbranch_vccz .Lmla_exp
	s_and_saveexec_b64 s[2:3], s[38:39]
	ds_write_b32 v176, v188 offset:128
	s_or_b64 exec, exec, s[2:3]
	s_waitcnt lgkmcnt(0)
	v_add_u32_e32 v190, v173, v196
	ds_read_b128 v[198:201], v190 offset:224
	ds_read_b128 v[214:217], v190 offset:192
	ds_read_b128 v[218:221], v190 offset:160
	ds_read_b128 v[222:225], v190 offset:128
	s_waitcnt lgkmcnt(3)
	v_pk_mul_f32 v[12:13], v[12:13], v[198:199]
	s_waitcnt lgkmcnt(2)
	v_pk_mul_f32 v[8:9], v[8:9], v[214:215]
	s_waitcnt lgkmcnt(1)
	v_pk_mul_f32 v[4:5], v[4:5], v[218:219]
	v_pk_mul_f32 v[14:15], v[14:15], v[200:201]
	v_pk_mul_f32 v[10:11], v[10:11], v[216:217]
	v_pk_mul_f32 v[6:7], v[6:7], v[220:221]
	s_waitcnt lgkmcnt(0)
	v_pk_mul_f32 v[2:3], v[2:3], v[224:225]
	v_pk_mul_f32 v[0:1], v[0:1], v[222:223]
	v_pk_mul_f32 v[60:61], v[60:61], v[198:199]
	v_pk_mul_f32 v[56:57], v[56:57], v[214:215]
	v_pk_mul_f32 v[52:53], v[52:53], v[218:219]
	v_pk_mul_f32 v[62:63], v[62:63], v[200:201]
	v_pk_mul_f32 v[58:59], v[58:59], v[216:217]
	v_pk_mul_f32 v[54:55], v[54:55], v[220:221]
	v_pk_mul_f32 v[50:51], v[50:51], v[224:225]
	v_pk_mul_f32 v[48:49], v[48:49], v[222:223]
	v_pk_mul_f32 v[44:45], v[44:45], v[198:199]
	v_pk_mul_f32 v[40:41], v[40:41], v[214:215]
	v_pk_mul_f32 v[36:37], v[36:37], v[218:219]
	v_pk_mul_f32 v[46:47], v[46:47], v[200:201]
	v_pk_mul_f32 v[42:43], v[42:43], v[216:217]
	v_pk_mul_f32 v[38:39], v[38:39], v[220:221]
	v_pk_mul_f32 v[34:35], v[34:35], v[224:225]
	v_pk_mul_f32 v[32:33], v[32:33], v[222:223]
	v_pk_mul_f32 v[28:29], v[28:29], v[198:199]
	v_pk_mul_f32 v[24:25], v[24:25], v[214:215]
	v_pk_mul_f32 v[20:21], v[20:21], v[218:219]
	v_pk_mul_f32 v[30:31], v[30:31], v[200:201]
	v_pk_mul_f32 v[26:27], v[26:27], v[216:217]
	v_pk_mul_f32 v[22:23], v[22:23], v[220:221]
	v_pk_mul_f32 v[18:19], v[18:19], v[224:225]
	v_pk_mul_f32 v[16:17], v[16:17], v[222:223]
	s_branch .Lmla_exp
